# PROJ_ODD P-tile epilogue: permlane swaps gather 8 bf16 per lane, 16 dwordx4 stores per wave instead of 32 dwordx2
# speedup vs baseline: 1.0039x; 1.0039x over previous
; DI unsigned pack2(float a, float b) { f32x2 v = {a, b}; return __builtin_bit_cast(unsigned, __builtin_convertvector(v, hwbf16x2)); }
; template <int EPI>
; DI void gemm8_epilogue(const GemmArgs& g, f32x4 (&acc)[2][2][4][2], const int brow, const int bcol, const int wr, const int wc, const int fr, const int fq) {
;     ...
;           bf16_t* P = (bf16_t*)g.out0;
; #pragma unroll
;           for (int n = 0; n < 2; ++n) {
;             const int col = cb + n * 16 + fq * 4;
; #pragma unroll
;             for (int m = 0; m < 4; ++m) {
;               u32x2 o; o.x = pack2(acc[ai][bj][m][n][0], acc[ai][bj][m][n][1]); o.y = pack2(acc[ai][bj][m][n][2], acc[ai][bj][m][n][3]);
;               *(u32x2*)&P[(size_t)(r0 + m * 16) * LDP_O + col] = o;
;             }
;           }
.LBB0_384:
	s_lshl_b32 s24, s23, 8
	s_lshl_b32 s23, s22, 8
	s_or_b32 s23, s23, s18
	s_add_i32 s24, s24, s17
	v_or_b32_e32 v140, s24, v148
	s_cmp_lt_i32 s22, 8
	s_cselect_b64 s[34:35], -1, 0
	v_or_b32_e32 v138, s23, v151
	v_or_b32_e32 v146, 16, v140
	v_or_b32_e32 v144, 32, v140
	v_or_b32_e32 v142, 48, v140
	s_mov_b64 s[40:41], -1
	s_and_b64 vcc, exec, s[34:35]
	v_ashrrev_i32_e32 v141, 31, v140
	v_ashrrev_i32_e32 v139, 31, v138
	v_ashrrev_i32_e32 v147, 31, v146
	v_ashrrev_i32_e32 v145, 31, v144
	v_ashrrev_i32_e32 v143, 31, v142
	s_cbranch_vccz .LBB0_386
	v_add_u32_e32 v154, v138, v151
	v_mov_b32_e32 v155, 0
	v_lshlrev_b64 v[156:157], 12, v[140:141]
	v_lshl_add_u64 v[154:155], v[154:155], 1, s[60:61]
	s_mov_b64 s[40:41], 0x10000
	s_mov_b64 s[50:51], 0x50000
	v_lshl_add_u64 v[154:155], v[154:155], 0, v[156:157]
	v_cvt_pk_bf16_f32 v126, v126, v127
	v_cvt_pk_bf16_f32 v127, v128, v129
	v_cvt_pk_bf16_f32 v128, v122, v123
	v_cvt_pk_bf16_f32 v129, v124, v125
	v_cvt_pk_bf16_f32 v94, v94, v95
	v_cvt_pk_bf16_f32 v95, v96, v97
	v_cvt_pk_bf16_f32 v96, v90, v91
	v_cvt_pk_bf16_f32 v97, v92, v93
	s_nop 1
	v_permlane32_swap_b32_e32 v126, v128
	v_permlane32_swap_b32_e32 v127, v129
	v_permlane32_swap_b32_e32 v94, v96
	v_permlane32_swap_b32_e32 v95, v97
	s_nop 1
	v_permlane16_swap_b32_e32 v126, v128
	v_permlane16_swap_b32_e32 v127, v129
	v_permlane16_swap_b32_e32 v94, v96
	v_permlane16_swap_b32_e32 v95, v97
	global_store_dwordx4 v[154:155], v[126:129], off
	global_store_dwordx4 v[154:155], v[94:97], off offset:256
	v_lshl_add_u64 v[154:155], v[154:155], 0, s[40:41]
	v_cvt_pk_bf16_f32 v118, v118, v119
	v_cvt_pk_bf16_f32 v119, v120, v121
	v_cvt_pk_bf16_f32 v120, v114, v115
	v_cvt_pk_bf16_f32 v121, v116, v117
	v_cvt_pk_bf16_f32 v86, v86, v87
	v_cvt_pk_bf16_f32 v87, v88, v89
	v_cvt_pk_bf16_f32 v88, v82, v83
	v_cvt_pk_bf16_f32 v89, v84, v85
	s_nop 1
	v_permlane32_swap_b32_e32 v118, v120
	v_permlane32_swap_b32_e32 v119, v121
	v_permlane32_swap_b32_e32 v86, v88
	v_permlane32_swap_b32_e32 v87, v89
	s_nop 1
	v_permlane16_swap_b32_e32 v118, v120
	v_permlane16_swap_b32_e32 v119, v121
	v_permlane16_swap_b32_e32 v86, v88
	v_permlane16_swap_b32_e32 v87, v89
	global_store_dwordx4 v[154:155], v[118:121], off
	global_store_dwordx4 v[154:155], v[86:89], off offset:256
	v_lshl_add_u64 v[154:155], v[154:155], 0, s[40:41]
	v_cvt_pk_bf16_f32 v110, v110, v111
	v_cvt_pk_bf16_f32 v111, v112, v113
	v_cvt_pk_bf16_f32 v112, v106, v107
	v_cvt_pk_bf16_f32 v113, v108, v109
	v_cvt_pk_bf16_f32 v78, v78, v79
	v_cvt_pk_bf16_f32 v79, v80, v81
	v_cvt_pk_bf16_f32 v80, v74, v75
	v_cvt_pk_bf16_f32 v81, v76, v77
	s_nop 1
	v_permlane32_swap_b32_e32 v110, v112
	v_permlane32_swap_b32_e32 v111, v113
	v_permlane32_swap_b32_e32 v78, v80
	v_permlane32_swap_b32_e32 v79, v81
	s_nop 1
	v_permlane16_swap_b32_e32 v110, v112
	v_permlane16_swap_b32_e32 v111, v113
	v_permlane16_swap_b32_e32 v78, v80
	v_permlane16_swap_b32_e32 v79, v81
	global_store_dwordx4 v[154:155], v[110:113], off
	global_store_dwordx4 v[154:155], v[78:81], off offset:256
	v_lshl_add_u64 v[154:155], v[154:155], 0, s[40:41]
	v_cvt_pk_bf16_f32 v102, v102, v103
	v_cvt_pk_bf16_f32 v103, v104, v105
	v_cvt_pk_bf16_f32 v104, v98, v99
	v_cvt_pk_bf16_f32 v105, v100, v101
	v_cvt_pk_bf16_f32 v70, v70, v71
	v_cvt_pk_bf16_f32 v71, v72, v73
	v_cvt_pk_bf16_f32 v72, v66, v67
	v_cvt_pk_bf16_f32 v73, v68, v69
	s_nop 1
	v_permlane32_swap_b32_e32 v102, v104
	v_permlane32_swap_b32_e32 v103, v105
	v_permlane32_swap_b32_e32 v70, v72
	v_permlane32_swap_b32_e32 v71, v73
	s_nop 1
	v_permlane16_swap_b32_e32 v102, v104
	v_permlane16_swap_b32_e32 v103, v105
	v_permlane16_swap_b32_e32 v70, v72
	v_permlane16_swap_b32_e32 v71, v73
	global_store_dwordx4 v[154:155], v[102:105], off
	global_store_dwordx4 v[154:155], v[70:73], off offset:256
	v_lshl_add_u64 v[154:155], v[154:155], 0, s[50:51]
	v_cvt_pk_bf16_f32 v62, v62, v63
	v_cvt_pk_bf16_f32 v63, v64, v65
	v_cvt_pk_bf16_f32 v64, v58, v59
	v_cvt_pk_bf16_f32 v65, v60, v61
	v_cvt_pk_bf16_f32 v30, v30, v31
	v_cvt_pk_bf16_f32 v31, v32, v33
	v_cvt_pk_bf16_f32 v32, v26, v27
	v_cvt_pk_bf16_f32 v33, v28, v29
	s_nop 1
	v_permlane32_swap_b32_e32 v62, v64
	v_permlane32_swap_b32_e32 v63, v65
	v_permlane32_swap_b32_e32 v30, v32
	v_permlane32_swap_b32_e32 v31, v33
	s_nop 1
	v_permlane16_swap_b32_e32 v62, v64
	v_permlane16_swap_b32_e32 v63, v65
	v_permlane16_swap_b32_e32 v30, v32
	v_permlane16_swap_b32_e32 v31, v33
	global_store_dwordx4 v[154:155], v[62:65], off
	global_store_dwordx4 v[154:155], v[30:33], off offset:256
	v_lshl_add_u64 v[154:155], v[154:155], 0, s[40:41]
	v_cvt_pk_bf16_f32 v54, v54, v55
	v_cvt_pk_bf16_f32 v55, v56, v57
	v_cvt_pk_bf16_f32 v56, v50, v51
	v_cvt_pk_bf16_f32 v57, v52, v53
	v_cvt_pk_bf16_f32 v22, v22, v23
	v_cvt_pk_bf16_f32 v23, v24, v25
	v_cvt_pk_bf16_f32 v24, v18, v19
	v_cvt_pk_bf16_f32 v25, v20, v21
	s_nop 1
	v_permlane32_swap_b32_e32 v54, v56
	v_permlane32_swap_b32_e32 v55, v57
	v_permlane32_swap_b32_e32 v22, v24
	v_permlane32_swap_b32_e32 v23, v25
	s_nop 1
	v_permlane16_swap_b32_e32 v54, v56
	v_permlane16_swap_b32_e32 v55, v57
	v_permlane16_swap_b32_e32 v22, v24
	v_permlane16_swap_b32_e32 v23, v25
	global_store_dwordx4 v[154:155], v[54:57], off
	global_store_dwordx4 v[154:155], v[22:25], off offset:256
	v_lshl_add_u64 v[154:155], v[154:155], 0, s[40:41]
	v_cvt_pk_bf16_f32 v46, v46, v47
	v_cvt_pk_bf16_f32 v47, v48, v49
	v_cvt_pk_bf16_f32 v48, v42, v43
	v_cvt_pk_bf16_f32 v49, v44, v45
	v_cvt_pk_bf16_f32 v14, v14, v15
	v_cvt_pk_bf16_f32 v15, v16, v17
	v_cvt_pk_bf16_f32 v16, v10, v11
	v_cvt_pk_bf16_f32 v17, v12, v13
	s_nop 1
	v_permlane32_swap_b32_e32 v46, v48
	v_permlane32_swap_b32_e32 v47, v49
	v_permlane32_swap_b32_e32 v14, v16
	v_permlane32_swap_b32_e32 v15, v17
	s_nop 1
	v_permlane16_swap_b32_e32 v46, v48
	v_permlane16_swap_b32_e32 v47, v49
	v_permlane16_swap_b32_e32 v14, v16
	v_permlane16_swap_b32_e32 v15, v17
	global_store_dwordx4 v[154:155], v[46:49], off
	global_store_dwordx4 v[154:155], v[14:17], off offset:256
	v_lshl_add_u64 v[154:155], v[154:155], 0, s[40:41]
	v_cvt_pk_bf16_f32 v38, v38, v39
	v_cvt_pk_bf16_f32 v39, v40, v41
	v_cvt_pk_bf16_f32 v40, v34, v35
	v_cvt_pk_bf16_f32 v41, v36, v37
	v_cvt_pk_bf16_f32 v6, v6, v7
	v_cvt_pk_bf16_f32 v7, v8, v9
	v_cvt_pk_bf16_f32 v8, v2, v3
	v_cvt_pk_bf16_f32 v9, v4, v5
	s_nop 1
	v_permlane32_swap_b32_e32 v38, v40
	v_permlane32_swap_b32_e32 v39, v41
	v_permlane32_swap_b32_e32 v6, v8
	v_permlane32_swap_b32_e32 v7, v9
	s_nop 1
	v_permlane16_swap_b32_e32 v38, v40
	v_permlane16_swap_b32_e32 v39, v41
	v_permlane16_swap_b32_e32 v6, v8
	v_permlane16_swap_b32_e32 v7, v9
	global_store_dwordx4 v[154:155], v[38:41], off
	global_store_dwordx4 v[154:155], v[6:9], off offset:256
	s_branch .LBB0_400
